# ROW_HG: hgrn_norm_g preloaded + gate-row chunk loads batched; MIX_O producer spurious vmcnt waits relaxed; stacked on ROW_GN/HG_H3/row_pre/ROW_P1/MIX_O edits
# speedup vs baseline: 1.0269x; 1.0076x over previous
.LBB0_952:
	s_add_i32 s6, s39, 0xffffff00
	s_cmpk_gt_i32 s39, 0xff
	s_cselect_b32 s52, s6, s39
	s_ashr_i32 s6, s52, 7
	s_lshl_b32 s7, s6, 3
	s_addk_i32 s7, 0x2000
	s_lshl_b32 s6, s6, 12
	s_cmpk_gt_i32 s39, 0xff
	s_cselect_b32 s28, 8, 0x1000
	s_cselect_b32 s6, s7, s6
	s_lshl_b32 s7, s35, 5
	s_sub_i32 s28, s28, s7
	s_min_i32 s34, s28, 32
	s_add_i32 s28, s6, s7
	s_bfe_u32 s38, s52, 0x50002
	s_cmpk_lt_i32 s39, 0x1100
	s_cselect_b64 s[6:7], -1, 0
	s_cmpk_gt_i32 s39, 0x10ff
	s_cbranch_scc1 .LBB0_960
	s_movk_i32 s54, 0x108
	s_ashr_i32 s55, s54, 31
	s_add_u32 s54, s0, s54
	s_addc_u32 s55, s1, s55
	s_load_dwordx2 s[54:55], s[54:55], 0x0
	v_readlane_b32 vcc_lo, v234, 50
	v_lshl_or_b32 v2, s38, 6, v0
	v_readlane_b32 vcc_hi, v234, 51
	s_movk_i32 s74, 0x110
	s_waitcnt lgkmcnt(0)
	s_add_u32 s54, s54, vcc_lo
	s_waitcnt vmcnt(2)
	v_lshlrev_b32_e32 v40, 2, v2
	s_addc_u32 s55, s55, vcc_hi
	global_load_dwordx4 v[4:7], v40, s[54:55]
	s_ashr_i32 s55, s74, 31
	s_add_u32 s54, s0, s74
	s_addc_u32 s55, s1, s55
	s_load_dwordx2 s[54:55], s[54:55], 0x0
	s_movk_i32 s74, 0x118
	s_waitcnt lgkmcnt(0)
	s_add_u32 s54, s54, vcc_lo
	s_addc_u32 s55, s55, vcc_hi
	global_load_dwordx4 v[24:27], v40, s[54:55]
	s_ashr_i32 s55, s74, 31
	s_add_u32 s54, s0, s74
	s_addc_u32 s55, s1, s55
	s_load_dwordx2 s[54:55], s[54:55], 0x0
	s_waitcnt lgkmcnt(0)
	s_add_u32 s54, s54, vcc_lo
	s_addc_u32 s55, s55, vcc_hi
	global_load_dwordx4 v[40:43], v40, s[54:55]
	v_cmp_gt_i32_e32 vcc, s34, v125
	s_and_saveexec_b64 s[54:55], vcc
	s_cbranch_execz .LBB0_956
	v_add_u32_e32 v8, s28, v125
	v_ashrrev_i32_e32 v9, 31, v8
	v_lshlrev_b64 v[8:9], 11, v[8:9]
	v_or_b32_e32 v8, v8, v2
	v_lshlrev_b64 v[76:77], 2, v[8:9]
	v_lshl_add_u64 v[8:9], s[10:11], 0, v[76:77]
	v_lshl_add_u64 v[16:17], s[12:13], 0, v[76:77]
	v_lshl_add_u64 v[28:29], s[14:15], 0, v[76:77]
	v_lshl_add_u64 v[32:33], s[18:19], 0, v[76:77]
	v_lshl_add_u64 v[36:37], s[20:21], 0, v[76:77]
	global_load_dwordx4 v[8:11], v[8:9], off
	s_nop 0
	global_load_dwordx4 v[16:19], v[16:17], off
	s_nop 0
	global_load_dwordx4 v[28:31], v[28:29], off
	s_nop 0
	global_load_dwordx4 v[32:35], v[32:33], off
	v_readlane_b32 s74, v234, 27
	global_load_dwordx4 v[36:39], v[36:37], off
	v_readlane_b32 s75, v234, 28
	s_andn2_b64 vcc, exec, s[74:75]
	s_cbranch_vccnz .LBB0_956
	v_lshl_add_u64 v[12:13], s[22:23], 0, v[76:77]
	v_lshl_add_u64 v[20:21], s[16:17], 0, v[76:77]
	global_load_dwordx4 v[12:15], v[12:13], off
	s_nop 0
	global_load_dwordx4 v[20:23], v[20:21], off
.LBB0_956:
	s_or_b64 exec, exec, s[54:55]
	v_cmp_gt_i32_e32 vcc, s34, v145
	s_and_saveexec_b64 s[54:55], vcc
	s_cbranch_execz .LBB0_959
	v_add_u32_e32 v44, s28, v145
	v_ashrrev_i32_e32 v45, 31, v44
	v_lshlrev_b64 v[44:45], 11, v[44:45]
	v_or_b32_e32 v44, v44, v2
	v_lshlrev_b64 v[76:77], 2, v[44:45]
	v_lshl_add_u64 v[44:45], s[10:11], 0, v[76:77]
	v_lshl_add_u64 v[48:49], s[12:13], 0, v[76:77]
	v_lshl_add_u64 v[60:61], s[14:15], 0, v[76:77]
	v_lshl_add_u64 v[64:65], s[18:19], 0, v[76:77]
	v_lshl_add_u64 v[68:69], s[20:21], 0, v[76:77]
	global_load_dwordx4 v[44:47], v[44:45], off
	s_nop 0
	global_load_dwordx4 v[48:51], v[48:49], off
	s_nop 0
	global_load_dwordx4 v[60:63], v[60:61], off
	s_nop 0
	global_load_dwordx4 v[64:67], v[64:65], off
	v_readlane_b32 s74, v234, 27
	global_load_dwordx4 v[68:71], v[68:69], off
	v_readlane_b32 s75, v234, 28
	s_andn2_b64 vcc, exec, s[74:75]
	s_cbranch_vccnz .LBB0_959
	v_lshl_add_u64 v[52:53], s[22:23], 0, v[76:77]
	v_lshl_add_u64 v[56:57], s[16:17], 0, v[76:77]
	global_load_dwordx4 v[52:55], v[52:53], off
	s_nop 0
	global_load_dwordx4 v[56:59], v[56:57], off

; __device__ __forceinline__ unsigned char* WSP() { return (unsigned char*)IN(41); }
; __device__ __forceinline__ int TID() { int t = threadIdx.x; asm volatile("" : "+v"(t)); return t; }
; __device__ __forceinline__ int BID() { int b = blockIdx.x; asm volatile("" : "+s"(b)); return b; }
; __device__ __forceinline__ int GSZ() { int g = gridDim.x; asm volatile("" : "+s"(g)); return g; }
; __device__ __forceinline__ int rfl(int v) { return __builtin_amdgcn_readfirstlane(v); }
; __device__ __forceinline__ void row_hg(const Params& p, int e) {
;     const int tid_ = TID(), lane = tid_ & 63, gw = BID() * 8 + rfl(tid_ >> 6), ngw = GSZ() * 8;
;     unsigned char* ws = WSP();
;     const float* O0 = (const float*)(ws + WS_OPART); const float* O1 = O0 + (size_t)M * 1024;
;     const float* PROJ = (const float*)(ws + WS_PROJ);
;     const float* g = IN(14) + (size_t)e * 1024;
;     bf16_t* MA = (bf16_t*)(ws + WS_MA);
;     for (int m = gw; m < M; m += ngw) {
.LBB0_998:
	s_and_b64 vcc, exec, s[2:3]
	s_cbranch_vccz .LBB0_1010
	s_waitcnt vmcnt(0)
	v_mov_b32_e32 v4, v146
	s_mov_b32 s2, s67
	s_lshl_b32 s2, s2, 3
	v_readfirstlane_b32 s3, v4
	s_ashr_i32 s3, s3, 6
	s_add_i32 s2, s3, s2
	s_load_dwordx2 s[4:5], s[0:1], 0x150
	s_waitcnt lgkmcnt(0)
	s_movk_i32 s5, 0x148
	s_movk_i32 s3, 0x70
	s_cmpk_gt_i32 s2, 0x20ff
	s_cbranch_scc1 .LBB0_1010
	v_and_b32_e32 v0, 64, v152
	v_add_u32_e32 v0, 64, v0
	v_xor_b32_e32 v1, 1, v152
	v_cmp_lt_i32_e32 vcc, v1, v0
	s_lshl_b32 s8, s4, 3
	s_ashr_i32 s7, s5, 31
	v_cndmask_b32_e32 v1, v152, v1, vcc
	v_lshlrev_b32_e32 v30, 2, v1
	v_xor_b32_e32 v1, 2, v152
	v_cmp_lt_i32_e32 vcc, v1, v0
	s_add_u32 s6, s0, s5
	s_addc_u32 s7, s1, s7
	v_cndmask_b32_e32 v1, v152, v1, vcc
	v_lshlrev_b32_e32 v31, 2, v1
	v_xor_b32_e32 v1, 4, v152
	v_cmp_lt_i32_e32 vcc, v1, v0
	s_ashr_i32 s5, s3, 31
	s_add_u32 s10, s0, s3
	v_cndmask_b32_e32 v1, v152, v1, vcc
	s_waitcnt vmcnt(1)
	v_lshlrev_b32_e32 v32, 2, v1
	v_xor_b32_e32 v1, 8, v152
	v_cmp_lt_i32_e32 vcc, v1, v0
	s_addc_u32 s11, s1, s5
	s_load_dwordx2 s[12:13], s[10:11], 0x0
	v_cndmask_b32_e32 v1, v152, v1, vcc
	v_lshlrev_b32_e32 v33, 2, v1
	v_xor_b32_e32 v1, 16, v152
	v_cmp_lt_i32_e32 vcc, v1, v0
	v_readlane_b32 s3, v234, 39
	s_load_dwordx2 s[10:11], s[6:7], 0x0
	v_cndmask_b32_e32 v1, v152, v1, vcc
	v_lshlrev_b32_e32 v34, 2, v1
	v_xor_b32_e32 v1, 32, v152
	v_cmp_lt_i32_e32 vcc, v1, v0
	s_waitcnt lgkmcnt(0)
	s_add_u32 s6, s12, s3
	s_addc_u32 s7, s13, 0
	v_cndmask_b32_e32 v0, v152, v1, vcc
	v_lshlrev_b32_e32 v35, 2, v0
	v_lshlrev_b32_e32 v0, 4, v4
	v_and_b32_e32 v2, 0x3f0, v0
	s_ashr_i32 s3, s2, 31
	v_lshl_add_u64 v[0:1], s[6:7], 0, v[2:3]
	s_lshl_b64 s[6:7], s[2:3], 12
	v_and_b32_e32 v2, 63, v4
	s_waitcnt vmcnt(0)
	v_lshl_or_b32 v20, v2, 3, s6
	s_ashr_i32 s9, s8, 31
	s_mul_hi_i32 s3, s2, 0x5800
	s_mul_i32 s5, s2, 0x5800
	v_lshlrev_b32_e32 v2, 4, v2
	v_mov_b32_e32 v21, s7
	s_lshl_b64 s[12:13], s[8:9], 12
	v_or_b32_e32 v22, s5, v2
	v_mov_b32_e32 v23, s3
	s_mul_i32 s14, s4, 0x2c000
	s_mul_hi_i32 s15, s8, 0x5800
	v_or_b32_e32 v24, s6, v2
	v_mov_b32_e32 v25, s7
	global_load_dwordx4 v[60:63], v[0:1], off
	global_load_dwordx4 v[64:67], v[0:1], off offset:1024
	global_load_dwordx4 v[68:71], v[0:1], off offset:2048
	global_load_dwordx4 v[72:75], v[0:1], off offset:3072
	s_branch .LBB0_1002
; __device__ __forceinline__ unsigned pk2(float lo, float hi) { f32x2c v = {lo, hi}; return __builtin_bit_cast(unsigned, __builtin_convertvector(v, bf16x2c)); }
; __device__ __forceinline__ float sigmoidf_(float x) { return __builtin_amdgcn_rcpf(1.0f + __expf(-x)); }
; __device__ __forceinline__ void row_hg(const Params& p, int e) {
;     ...
;         f32x4 v[4]; float s = 0.f;
; #pragma unroll
;         for (int j = 0; j < 4; ++j) { v[j] = *(const f32x4*)(O0 + (size_t)m * 1024 + 256 * j + 4 * lane); if (m >= MP) v[j] += *(const f32x4*)(O1 + (size_t)m * 1024 + 256 * j + 4 * lane);
;             s += (v[j][0] * v[j][0] + v[j][1] * v[j][1]) + (v[j][2] * v[j][2] + v[j][3] * v[j][3]); }
;         const float rs = rsqrtf(wave_sum(s) * (1.f / 1024.f) + 1e-6f);
; #pragma unroll
;         for (int j = 0; j < 4; ++j) { const f32x4 gg = *(const f32x4*)(g + 256 * j + 4 * lane); const f32x4 ga = *(const f32x4*)(PROJ + (size_t)m * IN_EVEN + 3072 + 256 * j + 4 * lane);
;             f32x4 y = v[j] * rs * gg;
; #pragma unroll
;             for (int q = 0; q < 4; ++q) y[q] *= ga[q] * sigmoidf_(ga[q]);
;             u32x2 w; w.x = pk2(y[0], y[1]); w.y = pk2(y[2], y[3]); *(u32x2*)(MA + (size_t)m * D + 256 * j + 4 * lane) = w; }
.LBB0_1001:
	s_waitcnt vmcnt(3)
	v_mul_f32_e32 v2, v17, v17
	v_mul_f32_e32 v26, v19, v19
	v_fmac_f32_e32 v2, v16, v16
	v_fmac_f32_e32 v26, v18, v18
	v_add_f32_e32 v2, v2, v26
	s_waitcnt vmcnt(2)
	v_mul_f32_e32 v26, v13, v13
	v_mul_f32_e32 v27, v15, v15
	v_fmac_f32_e32 v26, v12, v12
	v_fmac_f32_e32 v27, v14, v14
	v_add_f32_e32 v26, v26, v27
	v_add_f32_e32 v2, v2, v26
	s_waitcnt vmcnt(1)
	v_mul_f32_e32 v26, v9, v9
	v_mul_f32_e32 v27, v11, v11
	v_fmac_f32_e32 v26, v8, v8
	v_fmac_f32_e32 v27, v10, v10
	v_add_f32_e32 v26, v26, v27
	v_add_f32_e32 v2, v2, v26
	s_waitcnt vmcnt(0)
	v_pk_mul_f32 v[26:27], v[6:7], v[6:7]
	v_pk_mul_f32 v[28:29], v[4:5], v[4:5]
	s_mov_b32 s3, 0x1b203000
	v_pk_mov_b32 v[36:37], v[28:29], v[26:27] op_sel:[1,0]
	v_mov_b32_e32 v29, v27
	v_pk_add_f32 v[26:27], v[36:37], v[28:29]
	v_add_f32_e32 v26, v26, v27
	v_add_f32_e32 v2, v2, v26
	ds_bpermute_b32 v26, v30, v2
	v_lshl_add_u64 v[28:29], s[10:11], 0, v[20:21]
	s_add_i32 s2, s2, s8
	v_lshl_add_u64 v[20:21], v[20:21], 0, s[12:13]
	v_lshl_add_u64 v[24:25], v[24:25], 0, s[12:13]
	s_waitcnt lgkmcnt(0)
	v_add_f32_e32 v2, v2, v26
	ds_bpermute_b32 v26, v31, v2
	s_cmpk_gt_i32 s2, 0x20ff
	s_waitcnt lgkmcnt(0)
	v_add_f32_e32 v2, v2, v26
	ds_bpermute_b32 v26, v32, v2
	s_waitcnt lgkmcnt(0)
	v_add_f32_e32 v2, v2, v26
	ds_bpermute_b32 v26, v33, v2
	s_waitcnt lgkmcnt(0)
	v_add_f32_e32 v2, v2, v26
	ds_bpermute_b32 v26, v34, v2
	s_waitcnt lgkmcnt(0)
	v_add_f32_e32 v2, v2, v26
	ds_bpermute_b32 v26, v35, v2
	s_waitcnt lgkmcnt(0)
	v_add_f32_e32 v2, v2, v26
	v_fmamk_f32 v2, v2, 0x3a800000, v147
	v_cmp_gt_f32_e32 vcc, s29, v2
	v_mul_f32_e32 v26, 0x4b800000, v2
	s_nop 0
	v_cndmask_b32_e32 v2, v2, v26, vcc
	v_rsq_f32_e32 v2, v2
	s_nop 0
	v_mul_f32_e32 v26, 0x45800000, v2
	v_cndmask_b32_e32 v2, v2, v26, vcc
	v_lshl_add_u64 v[26:27], s[10:11], 0, v[22:23]
	v_add_co_u32_e32 v26, vcc, s3, v26
	v_pk_mul_f32 v[16:17], v[16:17], v[2:3] op_sel_hi:[1,0]
	s_nop 0
	v_addc_co_u32_e32 v27, vcc, 0, v27, vcc
	global_load_dwordx4 v[80:83], v[26:27], off
	global_load_dwordx4 v[84:87], v[26:27], off offset:1024
	global_load_dwordx4 v[88:91], v[26:27], off offset:2048
	global_load_dwordx4 v[92:95], v[26:27], off offset:3072
	v_pk_mul_f32 v[18:19], v[18:19], v[2:3] op_sel_hi:[1,0]
	v_pk_mul_f32 v[12:13], v[12:13], v[2:3] op_sel_hi:[1,0]
	v_pk_mul_f32 v[14:15], v[14:15], v[2:3] op_sel_hi:[1,0]
	v_pk_mul_f32 v[8:9], v[8:9], v[2:3] op_sel_hi:[1,0]
	v_pk_mul_f32 v[10:11], v[10:11], v[2:3] op_sel_hi:[1,0]
	v_pk_mul_f32 v[4:5], v[4:5], v[2:3] op_sel_hi:[1,0]
	v_pk_mul_f32 v[6:7], v[6:7], v[2:3] op_sel_hi:[1,0]
	v_lshl_add_u64 v[22:23], v[22:23], 0, s[14:15]
	v_pk_mul_f32 v[16:17], v[60:61], v[16:17]
	v_pk_mul_f32 v[18:19], v[62:63], v[18:19]
	s_waitcnt vmcnt(3)
	v_mul_f32_e32 v36, 0xbfb8aa3b, v80
	v_mul_f32_e32 v37, 0xbfb8aa3b, v81
	v_exp_f32_e32 v36, v36
	v_exp_f32_e32 v37, v37
	v_add_f32_e32 v36, 1.0, v36
	v_add_f32_e32 v37, 1.0, v37
	v_rcp_f32_e32 v36, v36
	v_rcp_f32_e32 v37, v37
	s_nop 0
	v_pk_mul_f32 v[36:37], v[80:81], v[36:37]
	s_nop 0
	v_pk_mul_f32 v[16:17], v[36:37], v[16:17]
	v_mul_f32_e32 v36, 0xbfb8aa3b, v82
	v_mul_f32_e32 v37, 0xbfb8aa3b, v83
	v_exp_f32_e32 v36, v36
	v_exp_f32_e32 v37, v37
	v_add_f32_e32 v36, 1.0, v36
	v_add_f32_e32 v37, 1.0, v37
	v_rcp_f32_e32 v36, v36
	v_rcp_f32_e32 v37, v37
	s_nop 0
	v_pk_mul_f32 v[36:37], v[82:83], v[36:37]
	s_nop 0
	v_pk_mul_f32 v[36:37], v[36:37], v[18:19]
	v_cvt_pk_bf16_f32 v18, v16, v17
	v_add_co_u32_e32 v16, vcc, s61, v28
	v_cvt_pk_bf16_f32 v19, v36, v37
	s_nop 0
	v_addc_co_u32_e32 v17, vcc, 0, v29, vcc
	global_store_dwordx2 v[16:17], v[18:19], off
	v_pk_mul_f32 v[12:13], v[64:65], v[12:13]
	s_waitcnt vmcnt(3)
	v_mul_f32_e32 v18, 0xbfb8aa3b, v84
	v_mul_f32_e32 v19, 0xbfb8aa3b, v85
	v_exp_f32_e32 v18, v18
	v_exp_f32_e32 v19, v19
	v_pk_mul_f32 v[14:15], v[66:67], v[14:15]
	v_add_f32_e32 v18, 1.0, v18
	v_add_f32_e32 v19, 1.0, v19
	v_rcp_f32_e32 v18, v18
	v_rcp_f32_e32 v19, v19
	s_nop 0
	v_pk_mul_f32 v[18:19], v[84:85], v[18:19]
	s_nop 0
	v_pk_mul_f32 v[12:13], v[18:19], v[12:13]
	v_mul_f32_e32 v18, 0xbfb8aa3b, v86
	v_mul_f32_e32 v19, 0xbfb8aa3b, v87
	v_exp_f32_e32 v18, v18
	v_exp_f32_e32 v19, v19
	v_cvt_pk_bf16_f32 v12, v12, v13
	v_add_f32_e32 v18, 1.0, v18
	v_add_f32_e32 v19, 1.0, v19
	v_rcp_f32_e32 v18, v18
	v_rcp_f32_e32 v19, v19
	s_nop 0
	v_pk_mul_f32 v[18:19], v[86:87], v[18:19]
	s_nop 0
	v_pk_mul_f32 v[14:15], v[18:19], v[14:15]
	s_nop 0
	v_cvt_pk_bf16_f32 v13, v14, v15
	global_store_dwordx2 v[16:17], v[12:13], off offset:512
	s_nop 0
	v_pk_mul_f32 v[8:9], v[68:69], v[8:9]
	s_waitcnt vmcnt(3)
	v_mul_f32_e32 v12, 0xbfb8aa3b, v88
	v_mul_f32_e32 v13, 0xbfb8aa3b, v89
	v_exp_f32_e32 v12, v12
	v_exp_f32_e32 v13, v13
	v_pk_mul_f32 v[10:11], v[70:71], v[10:11]
	v_add_f32_e32 v12, 1.0, v12
	v_add_f32_e32 v13, 1.0, v13
	v_rcp_f32_e32 v12, v12
	v_rcp_f32_e32 v13, v13
	s_nop 0
	v_pk_mul_f32 v[12:13], v[88:89], v[12:13]
	s_nop 0
	v_pk_mul_f32 v[8:9], v[12:13], v[8:9]
	v_mul_f32_e32 v12, 0xbfb8aa3b, v90
	v_mul_f32_e32 v13, 0xbfb8aa3b, v91
	v_exp_f32_e32 v12, v12
	v_exp_f32_e32 v13, v13
	v_cvt_pk_bf16_f32 v8, v8, v9
	v_add_f32_e32 v12, 1.0, v12
	v_add_f32_e32 v13, 1.0, v13
	v_rcp_f32_e32 v12, v12
	v_rcp_f32_e32 v13, v13
	s_nop 0
	v_pk_mul_f32 v[12:13], v[90:91], v[12:13]
	s_nop 0
	v_pk_mul_f32 v[10:11], v[12:13], v[10:11]
	s_nop 0
	v_cvt_pk_bf16_f32 v9, v10, v11
	global_store_dwordx2 v[16:17], v[8:9], off offset:1024
	s_nop 0
	v_pk_mul_f32 v[4:5], v[72:73], v[4:5]
	s_waitcnt vmcnt(3)
	v_mul_f32_e32 v2, 0xbfb8aa3b, v92
	v_exp_f32_e32 v2, v2
	v_pk_mul_f32 v[6:7], v[74:75], v[6:7]
	v_add_f32_e32 v2, 1.0, v2
	v_rcp_f32_e32 v8, v2
	v_mul_f32_e32 v2, 0xbfb8aa3b, v93
	v_exp_f32_e32 v2, v2
	s_nop 0
	v_add_f32_e32 v2, 1.0, v2
	v_rcp_f32_e32 v9, v2
	v_mul_f32_e32 v2, 0xbfb8aa3b, v94
	v_exp_f32_e32 v2, v2
	v_pk_mul_f32 v[8:9], v[92:93], v[8:9]
	s_nop 0
	v_pk_mul_f32 v[4:5], v[4:5], v[8:9]
	v_add_f32_e32 v2, 1.0, v2
	v_rcp_f32_e32 v8, v2
	v_mul_f32_e32 v2, 0xbfb8aa3b, v95
	v_exp_f32_e32 v2, v2
	v_cvt_pk_bf16_f32 v4, v4, v5
	v_add_f32_e32 v2, 1.0, v2
	v_rcp_f32_e32 v9, v2
	s_nop 0
	v_pk_mul_f32 v[8:9], v[94:95], v[8:9]
	s_nop 0
	v_pk_mul_f32 v[6:7], v[6:7], v[8:9]
	s_nop 0
	v_cvt_pk_bf16_f32 v5, v6, v7
	global_store_dwordx2 v[16:17], v[4:5], off offset:1536
	s_cbranch_scc1 .LBB0_1010
